# speedup vs baseline: 1.0026x; 1.0015x over previous
; #define SBAR() __builtin_amdgcn_sched_barrier(0)
; #define HBAR(n) do { asm volatile("s_waitcnt vmcnt(" #n ") lgkmcnt(0)" ::: "memory"); __builtin_amdgcn_s_barrier(); asm volatile("" ::: "memory"); } while (0)
; #define RD2(S, k, D0) do { S##l##k = tr_read<v_rd_off(D0, k, 0)>(vb); S##h##k = tr_read<v_rd_off(D0, k, 1)>(vb); } while (0)
; #define PVB(X, Y, D0, D1) do { LW(6); MF(X, 0, D0, pa0); SBAR(); RD2(Y, 0, D1); LW(6); MF(X, 1, D0, pa1); SBAR(); RD2(Y, 1, D1); \
;     LW(6); MF(X, 2, D0, pa2); SBAR(); RD2(Y, 2, D1); LW(6); MF(X, 3, D0, pa3); SBAR(); RD2(Y, 3, D1); } while (0)
; __device__ __forceinline__ void finishSM(f32x16& p0, f32x16& p1, float alpha, float& l_reg, bf16x8& pa0, bf16x8& pa1, bf16x8& pa2, bf16x8& pa3) {
;     ...
;     PK4(p0, 0, pa0); PK4(p0, 8, pa1); PK4(p1, 0, pa2); PK4(p1, 8, pa3);
; __device__ __forceinline__ void attn_dense_body(const bf16_t* __restrict__ Qb, const bf16_t* __restrict__ Kh, const bf16_t* __restrict__ Vh,
;                                                 float* __restrict__ Ob, int seq, char* lds, LAS unsigned char* lds3, const int tid) {
;     ...
;         const int vb = vb0 + b * (int)SHM_V;
;         s16x4 Al0, Ah0, Al1, Ah1, Al2, Ah2, Al3, Ah3, Bl0, Bh0, Bl1, Bh1, Bl2, Bh2, Bl3, Bh3;
;     ...
;         HBAR(6);
;         SBAR();
;         {
;     ...
;           __builtin_amdgcn_s_setprio(1);
;           RD2(A, 0, 0); RD2(A, 1, 0); RD2(A, 2, 0); RD2(A, 3, 0);
;           PVB(A, B, 0, 1); PVB(B, A, 1, 2); PVB(A, B, 2, 3); PVB(B, A, 3, 4); PVB(A, B, 4, 5); PVB(B, A, 5, 6); PVB(A, B, 6, 7);
.Lat_cont:
	v_add_f32_e32 v245, v245, v0
	v_add_f32_e32 v229, v229, v14
	v_lshl_add_u32 v14, s91, 15, v247
	v_cvt_pk_bf16_f32 v2, v160, v161
	v_cvt_pk_bf16_f32 v3, v162, v163
	ds_read_b64_tr_b16 v[160:161], v14 offset:0
	ds_read_b64_tr_b16 v[162:163], v14 offset:8192
	v_cvt_pk_bf16_f32 v10, v164, v165
	v_cvt_pk_bf16_f32 v11, v166, v167
	ds_read_b64_tr_b16 v[164:165], v14 offset:256
	ds_read_b64_tr_b16 v[166:167], v14 offset:8448
	v_cvt_pk_bf16_f32 v4, v168, v169
	v_cvt_pk_bf16_f32 v5, v170, v171
	ds_read_b64_tr_b16 v[168:169], v14 offset:512
	ds_read_b64_tr_b16 v[170:171], v14 offset:8704
	v_cvt_pk_bf16_f32 v12, v172, v173
	v_cvt_pk_bf16_f32 v13, v174, v175
	ds_read_b64_tr_b16 v[172:173], v14 offset:768
	ds_read_b64_tr_b16 v[174:175], v14 offset:8960
	v_cvt_pk_bf16_f32 v6, v176, v177
	v_cvt_pk_bf16_f32 v7, v178, v179
	ds_read_b64_tr_b16 v[176:177], v14 offset:1024
	ds_read_b64_tr_b16 v[178:179], v14 offset:9216
	v_cvt_pk_bf16_f32 v152, v180, v181
	v_cvt_pk_bf16_f32 v153, v182, v183
	ds_read_b64_tr_b16 v[180:181], v14 offset:1280
	ds_read_b64_tr_b16 v[182:183], v14 offset:9472
	v_cvt_pk_bf16_f32 v8, v184, v185
	v_cvt_pk_bf16_f32 v9, v186, v187
	ds_read_b64_tr_b16 v[184:185], v14 offset:1536
	ds_read_b64_tr_b16 v[186:187], v14 offset:9728
	v_cvt_pk_bf16_f32 v154, v188, v189
	v_cvt_pk_bf16_f32 v155, v190, v191
	ds_read_b64_tr_b16 v[188:189], v14 offset:1792
	ds_read_b64_tr_b16 v[190:191], v14 offset:9984
	v_lshl_add_u32 v232, s99, 14, v246
	v_add_u32_e32 v0, v239, v232
	v_xad_u32 v15, v239, 64, v232
	v_xad_u32 v231, v239, s60, v232
	s_movk_i32 s0, 0xc0
	v_xad_u32 v232, v239, s0, v232
	s_waitcnt vmcnt(6) lgkmcnt(0)
	s_barrier
	s_setprio 1
	v_mfma_f32_16x16x32_bf16 v[16:19], v[2:5], v[160:163], v[16:19]
	v_mfma_f32_16x16x32_bf16 v[80:83], v[10:13], v[160:163], v[80:83]
	v_mfma_f32_16x16x32_bf16 v[20:23], v[2:5], v[164:167], v[20:23]
	ds_read_b64_tr_b16 v[160:161], v14 offset:16384
	v_mfma_f32_16x16x32_bf16 v[84:87], v[10:13], v[164:167], v[84:87]
	ds_read_b64_tr_b16 v[162:163], v14 offset:24576
	v_mfma_f32_16x16x32_bf16 v[24:27], v[2:5], v[168:171], v[24:27]
	ds_read_b64_tr_b16 v[164:165], v14 offset:16640
	v_mfma_f32_16x16x32_bf16 v[88:91], v[10:13], v[168:171], v[88:91]
	ds_read_b64_tr_b16 v[166:167], v14 offset:24832
	v_mfma_f32_16x16x32_bf16 v[28:31], v[2:5], v[172:175], v[28:31]
	ds_read_b64_tr_b16 v[168:169], v14 offset:16896
	v_mfma_f32_16x16x32_bf16 v[92:95], v[10:13], v[172:175], v[92:95]
	ds_read_b64_tr_b16 v[170:171], v14 offset:25088
	v_mfma_f32_16x16x32_bf16 v[32:35], v[2:5], v[176:179], v[32:35]
	ds_read_b64_tr_b16 v[172:173], v14 offset:17152
	v_mfma_f32_16x16x32_bf16 v[96:99], v[10:13], v[176:179], v[96:99]
	ds_read_b64_tr_b16 v[174:175], v14 offset:25344
	v_mfma_f32_16x16x32_bf16 v[36:39], v[2:5], v[180:183], v[36:39]
	ds_read_b64_tr_b16 v[176:177], v14 offset:17408
	v_mfma_f32_16x16x32_bf16 v[100:103], v[10:13], v[180:183], v[100:103]
	ds_read_b64_tr_b16 v[178:179], v14 offset:25600
	v_mfma_f32_16x16x32_bf16 v[40:43], v[2:5], v[184:187], v[40:43]
	ds_read_b64_tr_b16 v[180:181], v14 offset:17664
	v_mfma_f32_16x16x32_bf16 v[104:107], v[10:13], v[184:187], v[104:107]
	ds_read_b64_tr_b16 v[182:183], v14 offset:25856
	v_mfma_f32_16x16x32_bf16 v[44:47], v[2:5], v[188:191], v[44:47]
	ds_read_b64_tr_b16 v[184:185], v14 offset:17920
	v_mfma_f32_16x16x32_bf16 v[108:111], v[10:13], v[188:191], v[108:111]
	ds_read_b64_tr_b16 v[186:187], v14 offset:26112
	s_waitcnt lgkmcnt(10)
	v_mfma_f32_16x16x32_bf16 v[16:19], v[6:9], v[160:163], v[16:19]
	ds_read_b64_tr_b16 v[188:189], v14 offset:18176
	v_mfma_f32_16x16x32_bf16 v[80:83], v[152:155], v[160:163], v[80:83]
	ds_read_b64_tr_b16 v[190:191], v14 offset:26368
	v_mfma_f32_16x16x32_bf16 v[20:23], v[6:9], v[164:167], v[20:23]
	ds_read_b64_tr_b16 v[160:161], v14 offset:2048
	v_mfma_f32_16x16x32_bf16 v[84:87], v[152:155], v[164:167], v[84:87]
	ds_read_b64_tr_b16 v[162:163], v14 offset:10240
	s_waitcnt lgkmcnt(10)
	v_mfma_f32_16x16x32_bf16 v[24:27], v[6:9], v[168:171], v[24:27]
	ds_read_b64_tr_b16 v[164:165], v14 offset:18432
	v_mfma_f32_16x16x32_bf16 v[88:91], v[152:155], v[168:171], v[88:91]
	ds_read_b64_tr_b16 v[166:167], v14 offset:26624
	v_mfma_f32_16x16x32_bf16 v[28:31], v[6:9], v[172:175], v[28:31]
	ds_read_b64_tr_b16 v[168:169], v14 offset:2304
	v_mfma_f32_16x16x32_bf16 v[92:95], v[152:155], v[172:175], v[92:95]
	ds_read_b64_tr_b16 v[170:171], v14 offset:10496
	s_waitcnt lgkmcnt(10)
	v_mfma_f32_16x16x32_bf16 v[32:35], v[6:9], v[176:179], v[32:35]
	ds_read_b64_tr_b16 v[172:173], v14 offset:18688
	v_mfma_f32_16x16x32_bf16 v[96:99], v[152:155], v[176:179], v[96:99]
	ds_read_b64_tr_b16 v[174:175], v14 offset:26880
	v_mfma_f32_16x16x32_bf16 v[36:39], v[6:9], v[180:183], v[36:39]
	ds_read_b64_tr_b16 v[176:177], v14 offset:2560
	v_mfma_f32_16x16x32_bf16 v[100:103], v[152:155], v[180:183], v[100:103]
	ds_read_b64_tr_b16 v[178:179], v14 offset:10752
	s_waitcnt lgkmcnt(10)
	v_mfma_f32_16x16x32_bf16 v[40:43], v[6:9], v[184:187], v[40:43]
	ds_read_b64_tr_b16 v[180:181], v14 offset:18944
	v_mfma_f32_16x16x32_bf16 v[104:107], v[152:155], v[184:187], v[104:107]
	ds_read_b64_tr_b16 v[182:183], v14 offset:27136
	v_mfma_f32_16x16x32_bf16 v[44:47], v[6:9], v[188:191], v[44:47]
	ds_read_b64_tr_b16 v[184:185], v14 offset:2816
	v_mfma_f32_16x16x32_bf16 v[108:111], v[152:155], v[188:191], v[108:111]
	ds_read_b64_tr_b16 v[186:187], v14 offset:11008
	s_waitcnt lgkmcnt(10)
; #define SBAR() __builtin_amdgcn_sched_barrier(0)
; #define KM(d0, B0, B1) do { p0 = __builtin_amdgcn_mfma_f32_32x32x16_bf16(B0, qr[d0], p0, 0, 0, 0); p1 = __builtin_amdgcn_mfma_f32_32x32x16_bf16(B1, qr[d0], p1, 0, 0, 0); } while (0)
; #define HBAR(n) do { asm volatile("s_waitcnt vmcnt(" #n ") lgkmcnt(0)" ::: "memory"); __builtin_amdgcn_s_barrier(); asm volatile("" ::: "memory"); } while (0)
; #define LW(n) do { asm volatile("s_waitcnt lgkmcnt(" #n ")" ::: "memory"); SBAR(); } while (0)
; #define RD2(S, k, D0) do { S##l##k = tr_read<v_rd_off(D0, k, 0)>(vb); S##h##k = tr_read<v_rd_off(D0, k, 1)>(vb); } while (0)
; #define LW(n) do { asm volatile("s_waitcnt lgkmcnt(" #n ")" ::: "memory"); SBAR(); } while (0)
; __device__ __forceinline__ void attn_dense_body(const bf16_t* __restrict__ Qb, const bf16_t* __restrict__ Kh, const bf16_t* __restrict__ Vh,
;                                                 float* __restrict__ Ob, int seq, char* lds, LAS unsigned char* lds3, const int tid) {
;     ...
;           __builtin_amdgcn_s_setprio(1);
;           RD2(A, 0, 0); RD2(A, 1, 0); RD2(A, 2, 0); RD2(A, 3, 0);
;           PVB(A, B, 0, 1); PVB(B, A, 1, 2); PVB(A, B, 2, 3); PVB(B, A, 3, 4); PVB(A, B, 4, 5); PVB(B, A, 5, 6); PVB(A, B, 6, 7);
;           const int kadr = (int)(uintptr_t)K_lds + b1 * (int)SHM_K + r32 * 256; int kt = (hi * 16) ^ ((r32 & 7) << 4);
;           asm volatile("" : "+v"(kt));
;           bf16x8 k0a, k0b, k1a, k1b, k2a, k2b;
;     ...
;           LW(6); MF(B, 0, 7, pa0); SBAR(); KRD(0, k0a, k0b);
;           LW(6); MF(B, 1, 7, pa1); SBAR(); KRD(1, k1a, k1b);
;           LW(6); MF(B, 2, 7, pa2); SBAR(); KRD(2, k2a, k2b);
;           LW(6); MF(B, 3, 7, pa3); SBAR();
;           LW(4); p0 = __builtin_amdgcn_mfma_f32_32x32x16_bf16(k0a, qr[0], nm, 0, 0, 0); p1 = __builtin_amdgcn_mfma_f32_32x32x16_bf16(k0b, qr[0], nm, 0, 0, 0); SBAR(); KRD(3, k0a, k0b);
;           LW(4); KM(1, k1a, k1b); SBAR(); KRD(4, k1a, k1b);
;           LW(4); KM(2, k2a, k2b); SBAR(); KRD(5, k2a, k2b);
;           LW(4); KM(3, k0a, k0b); SBAR(); KRD(6, k0a, k0b);
;           LW(4); KM(4, k1a, k1b); SBAR(); KRD(7, k1a, k1b);
;           LW(4); KM(5, k2a, k2b); SBAR();
;           LW(2); KM(6, k0a, k0b); SBAR();
;           LW(0); KM(7, k1a, k1b);
;           __builtin_amdgcn_s_setprio(0);
;     ...
;         }
;     ...
;         HBAR(0);
;         { const int t_ = b; b = b1; b1 = b2; b2 = t_; }
	v_mfma_f32_16x16x32_bf16 v[48:51], v[2:5], v[160:163], v[48:51]
	ds_read_b64_tr_b16 v[188:189], v14 offset:19200
	v_mfma_f32_16x16x32_bf16 v[112:115], v[10:13], v[160:163], v[112:115]
	ds_read_b64_tr_b16 v[190:191], v14 offset:27392
	v_mfma_f32_16x16x32_bf16 v[48:51], v[6:9], v[164:167], v[48:51]
	ds_read_b64_tr_b16 v[160:161], v14 offset:3072
	v_mfma_f32_16x16x32_bf16 v[112:115], v[152:155], v[164:167], v[112:115]
	ds_read_b64_tr_b16 v[162:163], v14 offset:11264
	s_waitcnt lgkmcnt(10)
	v_mfma_f32_16x16x32_bf16 v[52:55], v[2:5], v[168:171], v[52:55]
	ds_read_b64_tr_b16 v[164:165], v14 offset:19456
	v_mfma_f32_16x16x32_bf16 v[116:119], v[10:13], v[168:171], v[116:119]
	ds_read_b64_tr_b16 v[166:167], v14 offset:27648
	v_mfma_f32_16x16x32_bf16 v[52:55], v[6:9], v[172:175], v[52:55]
	ds_read_b64_tr_b16 v[168:169], v14 offset:3328
	v_mfma_f32_16x16x32_bf16 v[116:119], v[152:155], v[172:175], v[116:119]
	ds_read_b64_tr_b16 v[170:171], v14 offset:11520
	s_waitcnt lgkmcnt(10)
	v_mfma_f32_16x16x32_bf16 v[56:59], v[2:5], v[176:179], v[56:59]
	ds_read_b64_tr_b16 v[172:173], v14 offset:19712
	v_mfma_f32_16x16x32_bf16 v[120:123], v[10:13], v[176:179], v[120:123]
	ds_read_b64_tr_b16 v[174:175], v14 offset:27904
	v_mfma_f32_16x16x32_bf16 v[56:59], v[6:9], v[180:183], v[56:59]
	ds_read_b64_tr_b16 v[176:177], v14 offset:3584
	v_mfma_f32_16x16x32_bf16 v[120:123], v[152:155], v[180:183], v[120:123]
	ds_read_b64_tr_b16 v[178:179], v14 offset:11776
	s_waitcnt lgkmcnt(10)
	v_mfma_f32_16x16x32_bf16 v[60:63], v[2:5], v[184:187], v[60:63]
	ds_read_b64_tr_b16 v[180:181], v14 offset:19968
	v_mfma_f32_16x16x32_bf16 v[124:127], v[10:13], v[184:187], v[124:127]
	ds_read_b64_tr_b16 v[182:183], v14 offset:28160
	v_mfma_f32_16x16x32_bf16 v[60:63], v[6:9], v[188:191], v[60:63]
	ds_read_b64_tr_b16 v[184:185], v14 offset:3840
	v_mfma_f32_16x16x32_bf16 v[124:127], v[152:155], v[188:191], v[124:127]
	ds_read_b64_tr_b16 v[186:187], v14 offset:12032
	s_waitcnt lgkmcnt(10)
	v_mfma_f32_16x16x32_bf16 v[64:67], v[2:5], v[160:163], v[64:67]
	ds_read_b64_tr_b16 v[188:189], v14 offset:20224
	v_mfma_f32_16x16x32_bf16 v[128:131], v[10:13], v[160:163], v[128:131]
	ds_read_b64_tr_b16 v[190:191], v14 offset:28416
	v_mfma_f32_16x16x32_bf16 v[64:67], v[6:9], v[164:167], v[64:67]
	v_mfma_f32_16x16x32_bf16 v[128:131], v[152:155], v[164:167], v[128:131]
	s_waitcnt lgkmcnt(8)
	v_mfma_f32_16x16x32_bf16 v[68:71], v[2:5], v[168:171], v[68:71]
	v_mfma_f32_16x16x32_bf16 v[132:135], v[10:13], v[168:171], v[132:135]
	v_mfma_f32_16x16x32_bf16 v[68:71], v[6:9], v[172:175], v[68:71]
	v_mfma_f32_16x16x32_bf16 v[132:135], v[152:155], v[172:175], v[132:135]
	s_waitcnt lgkmcnt(4)
	v_mfma_f32_16x16x32_bf16 v[72:75], v[2:5], v[176:179], v[72:75]
	v_mfma_f32_16x16x32_bf16 v[136:139], v[10:13], v[176:179], v[136:139]
	ds_read_b128 v[156:159], v0 offset:0
	v_mfma_f32_16x16x32_bf16 v[72:75], v[6:9], v[180:183], v[72:75]
	v_mfma_f32_16x16x32_bf16 v[136:139], v[152:155], v[180:183], v[136:139]
	ds_read_b128 v[224:227], v15 offset:0
	s_waitcnt lgkmcnt(2)
	v_mfma_f32_16x16x32_bf16 v[76:79], v[2:5], v[184:187], v[76:79]
	v_mfma_f32_16x16x32_bf16 v[140:143], v[10:13], v[184:187], v[140:143]
	ds_read_b128 v[234:237], v231 offset:0
	v_mfma_f32_16x16x32_bf16 v[76:79], v[6:9], v[188:191], v[76:79]
	v_mfma_f32_16x16x32_bf16 v[140:143], v[152:155], v[188:191], v[140:143]
	ds_read_b128 v[248:251], v232 offset:0
	ds_read_b128 v[2:5], v0 offset:4096
	ds_read_b128 v[6:9], v15 offset:4096
	ds_read_b128 v[10:13], v231 offset:4096
	ds_read_b128 v[152:155], v232 offset:4096
	s_waitcnt lgkmcnt(7)
	v_mfma_f32_16x16x32_bf16 v[160:163], v[156:159], v[192:195], v[144:147]
	v_mfma_f32_16x16x32_bf16 v[164:167], v[156:159], v[208:211], v[148:151]
	ds_read_b128 v[156:159], v0 offset:8192
	s_waitcnt lgkmcnt(7)
	v_mfma_f32_16x16x32_bf16 v[160:163], v[224:227], v[196:199], v[160:163]
	v_mfma_f32_16x16x32_bf16 v[164:167], v[224:227], v[212:215], v[164:167]
	ds_read_b128 v[224:227], v15 offset:8192
	s_waitcnt lgkmcnt(7)
	v_mfma_f32_16x16x32_bf16 v[160:163], v[234:237], v[200:203], v[160:163]
	v_mfma_f32_16x16x32_bf16 v[164:167], v[234:237], v[216:219], v[164:167]
	ds_read_b128 v[234:237], v231 offset:8192
	s_waitcnt lgkmcnt(7)
	v_mfma_f32_16x16x32_bf16 v[160:163], v[248:251], v[204:207], v[160:163]
	v_mfma_f32_16x16x32_bf16 v[164:167], v[248:251], v[220:223], v[164:167]
	ds_read_b128 v[248:251], v232 offset:8192
	s_waitcnt lgkmcnt(7)
	v_mfma_f32_16x16x32_bf16 v[168:171], v[2:5], v[192:195], v[144:147]
	v_mfma_f32_16x16x32_bf16 v[172:175], v[2:5], v[208:211], v[148:151]
	ds_read_b128 v[2:5], v0 offset:12288
	s_waitcnt lgkmcnt(7)
	v_mfma_f32_16x16x32_bf16 v[168:171], v[6:9], v[196:199], v[168:171]
	v_mfma_f32_16x16x32_bf16 v[172:175], v[6:9], v[212:215], v[172:175]
	ds_read_b128 v[6:9], v15 offset:12288
	s_waitcnt lgkmcnt(7)
	v_mfma_f32_16x16x32_bf16 v[168:171], v[10:13], v[200:203], v[168:171]
	v_mfma_f32_16x16x32_bf16 v[172:175], v[10:13], v[216:219], v[172:175]
	ds_read_b128 v[10:13], v231 offset:12288
	s_waitcnt lgkmcnt(7)
	v_mfma_f32_16x16x32_bf16 v[168:171], v[152:155], v[204:207], v[168:171]
	v_mfma_f32_16x16x32_bf16 v[172:175], v[152:155], v[220:223], v[172:175]
	ds_read_b128 v[152:155], v232 offset:12288
	s_waitcnt lgkmcnt(7)
	v_mfma_f32_16x16x32_bf16 v[176:179], v[156:159], v[192:195], v[144:147]
	v_mfma_f32_16x16x32_bf16 v[180:183], v[156:159], v[208:211], v[148:151]
	s_waitcnt lgkmcnt(6)
	v_mfma_f32_16x16x32_bf16 v[176:179], v[224:227], v[196:199], v[176:179]
	v_mfma_f32_16x16x32_bf16 v[180:183], v[224:227], v[212:215], v[180:183]
	s_waitcnt lgkmcnt(5)
	v_mfma_f32_16x16x32_bf16 v[176:179], v[234:237], v[200:203], v[176:179]
	v_mfma_f32_16x16x32_bf16 v[180:183], v[234:237], v[216:219], v[180:183]
	s_waitcnt lgkmcnt(4)
	v_mfma_f32_16x16x32_bf16 v[176:179], v[248:251], v[204:207], v[176:179]
	v_mfma_f32_16x16x32_bf16 v[180:183], v[248:251], v[220:223], v[180:183]
	s_waitcnt lgkmcnt(3)
	v_mfma_f32_16x16x32_bf16 v[184:187], v[2:5], v[192:195], v[144:147]
	v_mfma_f32_16x16x32_bf16 v[188:191], v[2:5], v[208:211], v[148:151]
	s_waitcnt lgkmcnt(2)
	v_mfma_f32_16x16x32_bf16 v[184:187], v[6:9], v[196:199], v[184:187]
	v_mfma_f32_16x16x32_bf16 v[188:191], v[6:9], v[212:215], v[188:191]
	s_waitcnt lgkmcnt(1)
	v_mfma_f32_16x16x32_bf16 v[184:187], v[10:13], v[200:203], v[184:187]
	v_mfma_f32_16x16x32_bf16 v[188:191], v[10:13], v[216:219], v[188:191]
	s_waitcnt lgkmcnt(0)
	v_mfma_f32_16x16x32_bf16 v[184:187], v[152:155], v[204:207], v[184:187]
	v_mfma_f32_16x16x32_bf16 v[188:191], v[152:155], v[220:223], v[188:191]
	s_setprio 0
	s_waitcnt vmcnt(0) lgkmcnt(0)
	s_barrier
	s_cmp_eq_u32 s15, s89
	s_cbranch_scc1 .Lat_done
	s_mov_b32 s0, s99
	s_mov_b32 s99, s10
	s_mov_b32 s10, s91
	s_branch .Lat_loop
